# attention epilogue: all 16 sub-LN weight chunks fetched up front (was load->wait->store chain)
# speedup vs baseline: 1.0704x; 1.0010x over previous
.LBB0_274:
	s_or_b64 exec, exec, s[4:5]
	s_movk_i32 s1, 0x80
	v_cmp_gt_u32_e32 vcc, s1, v236
	s_waitcnt lgkmcnt(0)
	s_barrier
	s_and_saveexec_b64 s[4:5], vcc
	s_cbranch_execz .LBB0_276
	v_readlane_b32 s20, v255, 20
	v_readlane_b32 s21, v255, 21
	v_lshlrev_b32_e32 v68, 2, v184
	v_lshlrev_b32_e32 v69, 8, v236
	s_movk_i32 s1, 0x4000
	v_and_or_b32 v73, v69, s1, v68
	v_mov_b32_e32 v151, v1
	global_load_dword v72, v1, s[20:21]
	s_waitcnt vmcnt(4)
	ds_read2st64_b32 v[132:133], v73 offset1:1
	ds_read2st64_b32 v[118:119], v73 offset0:2 offset1:3
	ds_read2st64_b32 v[130:131], v73 offset0:4 offset1:5
	s_waitcnt vmcnt(3)
	ds_read2st64_b32 v[134:135], v73 offset0:6 offset1:7
	ds_read2st64_b32 v[126:127], v73 offset0:8 offset1:9
	ds_read2st64_b32 v[128:129], v73 offset0:10 offset1:11
	ds_read2st64_b32 v[122:123], v73 offset0:12 offset1:13
	ds_read2st64_b32 v[124:125], v73 offset0:14 offset1:15
	ds_read2st64_b32 v[116:117], v73 offset0:16 offset1:17
	ds_read2st64_b32 v[120:121], v73 offset0:18 offset1:19
	ds_read2st64_b32 v[112:113], v73 offset0:20 offset1:21
	ds_read2st64_b32 v[114:115], v73 offset0:22 offset1:23
	ds_read2st64_b32 v[108:109], v73 offset0:24 offset1:25
	ds_read2st64_b32 v[110:111], v73 offset0:26 offset1:27
	ds_read2st64_b32 v[104:105], v73 offset0:28 offset1:29
	ds_read2st64_b32 v[106:107], v73 offset0:30 offset1:31
	ds_read2st64_b32 v[100:101], v73 offset0:32 offset1:33
	ds_read2st64_b32 v[102:103], v73 offset0:34 offset1:35
	ds_read2st64_b32 v[96:97], v73 offset0:36 offset1:37
	ds_read2st64_b32 v[98:99], v73 offset0:38 offset1:39
	ds_read2st64_b32 v[92:93], v73 offset0:40 offset1:41
	ds_read2st64_b32 v[94:95], v73 offset0:42 offset1:43
	ds_read2st64_b32 v[88:89], v73 offset0:44 offset1:45
	ds_read2st64_b32 v[90:91], v73 offset0:46 offset1:47
	ds_read2st64_b32 v[84:85], v73 offset0:48 offset1:49
	ds_read2st64_b32 v[86:87], v73 offset0:50 offset1:51
	ds_read2st64_b32 v[80:81], v73 offset0:52 offset1:53
	ds_read2st64_b32 v[82:83], v73 offset0:54 offset1:55
	ds_read2st64_b32 v[76:77], v73 offset0:56 offset1:57
	ds_read2st64_b32 v[78:79], v73 offset0:58 offset1:59
	ds_read2st64_b32 v[66:67], v73 offset0:60 offset1:61
	s_movk_i32 s20, 0x3f00
	s_waitcnt vmcnt(0) lgkmcnt(0)
	v_pk_mul_f32 v[66:67], v[72:73], v[66:67] op_sel_hi:[0,1]
	v_pk_fma_f32 v[66:67], v[14:15], v[0:1], v[66:67] op_sel_hi:[1,0,1] neg_lo:[0,0,1] neg_hi:[0,0,1]
	v_or3_b32 v15, v69, v68, s20
	ds_read_b32 v14, v73 offset:15872
	ds_read_b32 v15, v15
	v_readlane_b32 s20, v255, 22
	v_readlane_b32 s21, v255, 23
	v_pk_mul_f32 v[70:71], v[66:67], v[66:67]
	s_waitcnt lgkmcnt(0)
	v_pk_mul_f32 v[14:15], v[72:73], v[14:15] op_sel_hi:[0,1]
	v_pk_fma_f32 v[68:69], v[16:17], v[0:1], v[14:15] op_sel_hi:[1,0,1] neg_lo:[0,0,1] neg_hi:[0,0,1]
	s_nop 0
	global_load_dword v73, v1, s[20:21]
	v_readlane_b32 s20, v252, 36
	v_readlane_b32 s21, v252, 37
	v_pk_mul_f32 v[74:75], v[68:69], v[68:69]
	s_waitcnt vmcnt(0)
	v_pk_mul_f32 v[130:131], v[72:73], v[130:131] op_sel_hi:[0,1]
	v_pk_fma_f32 v[130:131], v[54:55], v[0:1], v[130:131] op_sel_hi:[1,0,1] neg_lo:[0,0,1] neg_hi:[0,0,1]
	v_pk_mul_f32 v[54:55], v[72:73], v[128:129] op_sel_hi:[0,1]
	v_pk_fma_f32 v[54:55], v[60:61], v[0:1], v[54:55] op_sel_hi:[1,0,1] neg_lo:[0,0,1] neg_hi:[0,0,1]
	v_pk_mul_f32 v[60:61], v[72:73], v[126:127] op_sel_hi:[0,1]
	v_pk_fma_f32 v[60:61], v[58:59], v[0:1], v[60:61] op_sel_hi:[1,0,1] neg_lo:[0,0,1] neg_hi:[0,0,1]
	v_pk_mul_f32 v[58:59], v[72:73], v[124:125] op_sel_hi:[0,1]
	v_pk_fma_f32 v[58:59], v[64:65], v[0:1], v[58:59] op_sel_hi:[1,0,1] neg_lo:[0,0,1] neg_hi:[0,0,1]
	v_pk_mul_f32 v[64:65], v[72:73], v[122:123] op_sel_hi:[0,1]
	v_pk_fma_f32 v[62:63], v[62:63], v[0:1], v[64:65] op_sel_hi:[1,0,1] neg_lo:[0,0,1] neg_hi:[0,0,1]
	v_pk_mul_f32 v[64:65], v[72:73], v[120:121] op_sel_hi:[0,1]
	v_pk_fma_f32 v[36:37], v[36:37], v[0:1], v[64:65] op_sel_hi:[1,0,1] neg_lo:[0,0,1] neg_hi:[0,0,1]
	v_pk_mul_f32 v[64:65], v[72:73], v[116:117] op_sel_hi:[0,1]
	v_pk_fma_f32 v[64:65], v[34:35], v[0:1], v[64:65] op_sel_hi:[1,0,1] neg_lo:[0,0,1] neg_hi:[0,0,1]
	v_pk_mul_f32 v[34:35], v[72:73], v[114:115] op_sel_hi:[0,1]
	v_pk_fma_f32 v[34:35], v[40:41], v[0:1], v[34:35] op_sel_hi:[1,0,1] neg_lo:[0,0,1] neg_hi:[0,0,1]
	v_pk_mul_f32 v[40:41], v[72:73], v[112:113] op_sel_hi:[0,1]
	v_pk_fma_f32 v[38:39], v[38:39], v[0:1], v[40:41] op_sel_hi:[1,0,1] neg_lo:[0,0,1] neg_hi:[0,0,1]
	v_pk_mul_f32 v[40:41], v[72:73], v[110:111] op_sel_hi:[0,1]
	v_pk_fma_f32 v[110:111], v[44:45], v[0:1], v[40:41] op_sel_hi:[1,0,1] neg_lo:[0,0,1] neg_hi:[0,0,1]
	v_pk_mul_f32 v[40:41], v[72:73], v[108:109] op_sel_hi:[0,1]
	v_pk_fma_f32 v[108:109], v[42:43], v[0:1], v[40:41] op_sel_hi:[1,0,1] neg_lo:[0,0,1] neg_hi:[0,0,1]
	v_pk_mul_f32 v[40:41], v[72:73], v[106:107] op_sel_hi:[0,1]
	v_pk_fma_f32 v[48:49], v[48:49], v[0:1], v[40:41] op_sel_hi:[1,0,1] neg_lo:[0,0,1] neg_hi:[0,0,1]
	v_pk_mul_f32 v[40:41], v[72:73], v[104:105] op_sel_hi:[0,1]
	v_pk_fma_f32 v[104:105], v[46:47], v[0:1], v[40:41] op_sel_hi:[1,0,1] neg_lo:[0,0,1] neg_hi:[0,0,1]
	v_pk_mul_f32 v[40:41], v[72:73], v[102:103] op_sel_hi:[0,1]
	v_pk_fma_f32 v[42:43], v[20:21], v[0:1], v[40:41] op_sel_hi:[1,0,1] neg_lo:[0,0,1] neg_hi:[0,0,1]
	v_pk_mul_f32 v[20:21], v[72:73], v[100:101] op_sel_hi:[0,1]
	v_pk_fma_f32 v[46:47], v[18:19], v[0:1], v[20:21] op_sel_hi:[1,0,1] neg_lo:[0,0,1] neg_hi:[0,0,1]
	v_pk_mul_f32 v[18:19], v[72:73], v[98:99] op_sel_hi:[0,1]
	v_pk_fma_f32 v[40:41], v[24:25], v[0:1], v[18:19] op_sel_hi:[1,0,1] neg_lo:[0,0,1] neg_hi:[0,0,1]
	v_pk_mul_f32 v[18:19], v[72:73], v[96:97] op_sel_hi:[0,1]
	v_pk_fma_f32 v[44:45], v[22:23], v[0:1], v[18:19] op_sel_hi:[1,0,1] neg_lo:[0,0,1] neg_hi:[0,0,1]
	v_pk_mul_f32 v[18:19], v[72:73], v[94:95] op_sel_hi:[0,1]
	v_pk_fma_f32 v[24:25], v[28:29], v[0:1], v[18:19] op_sel_hi:[1,0,1] neg_lo:[0,0,1] neg_hi:[0,0,1]
	v_pk_mul_f32 v[18:19], v[72:73], v[92:93] op_sel_hi:[0,1]
	v_pk_fma_f32 v[28:29], v[26:27], v[0:1], v[18:19] op_sel_hi:[1,0,1] neg_lo:[0,0,1] neg_hi:[0,0,1]
	v_pk_mul_f32 v[18:19], v[72:73], v[90:91] op_sel_hi:[0,1]
	v_pk_fma_f32 v[20:21], v[32:33], v[0:1], v[18:19] op_sel_hi:[1,0,1] neg_lo:[0,0,1] neg_hi:[0,0,1]
	v_pk_mul_f32 v[18:19], v[72:73], v[88:89] op_sel_hi:[0,1]
	v_pk_fma_f32 v[26:27], v[30:31], v[0:1], v[18:19] op_sel_hi:[1,0,1] neg_lo:[0,0,1] neg_hi:[0,0,1]
	v_pk_mul_f32 v[18:19], v[72:73], v[86:87] op_sel_hi:[0,1]
	v_pk_fma_f32 v[18:19], v[4:5], v[0:1], v[18:19] op_sel_hi:[1,0,1] neg_lo:[0,0,1] neg_hi:[0,0,1]
	v_pk_mul_f32 v[4:5], v[72:73], v[84:85] op_sel_hi:[0,1]
	v_lshl_add_u64 v[14:15], s[20:21], 0, v[148:149]
	v_pk_mul_f32 v[132:133], v[72:73], v[132:133] op_sel_hi:[0,1]
	v_pk_fma_f32 v[22:23], v[2:3], v[0:1], v[4:5] op_sel_hi:[1,0,1] neg_lo:[0,0,1] neg_hi:[0,0,1]
	v_pk_mul_f32 v[2:3], v[72:73], v[82:83] op_sel_hi:[0,1]
	v_lshl_add_u64 v[138:139], v[14:15], 0, s[94:95]
	v_pk_mul_f32 v[14:15], v[72:73], v[118:119] op_sel_hi:[0,1]
	v_pk_fma_f32 v[132:133], v[50:51], v[0:1], v[132:133] op_sel_hi:[1,0,1] neg_lo:[0,0,1] neg_hi:[0,0,1]
	v_pk_fma_f32 v[4:5], v[8:9], v[0:1], v[2:3] op_sel_hi:[1,0,1] neg_lo:[0,0,1] neg_hi:[0,0,1]
	v_pk_mul_f32 v[2:3], v[72:73], v[80:81] op_sel_hi:[0,1]
	v_pk_fma_f32 v[52:53], v[52:53], v[0:1], v[14:15] op_sel_hi:[1,0,1] neg_lo:[0,0,1] neg_hi:[0,0,1]
	v_pk_mul_f32 v[136:137], v[132:133], v[132:133]
	v_pk_mul_f32 v[134:135], v[72:73], v[134:135] op_sel_hi:[0,1]
	v_pk_fma_f32 v[8:9], v[6:7], v[0:1], v[2:3] op_sel_hi:[1,0,1] neg_lo:[0,0,1] neg_hi:[0,0,1]
	v_pk_mul_f32 v[2:3], v[72:73], v[78:79] op_sel_hi:[0,1]
	v_pk_mul_f32 v[6:7], v[72:73], v[76:77] op_sel_hi:[0,1]
	v_pk_mul_f32 v[118:119], v[52:53], v[52:53]
	global_load_dwordx4 v[14:17], v146, s[28:29]
	global_load_dwordx4 v[152:155], v146, s[28:29] offset:32
	global_load_dwordx4 v[156:159], v146, s[28:29] offset:64
	global_load_dwordx4 v[160:163], v146, s[28:29] offset:96
	global_load_dwordx4 v[164:167], v146, s[28:29] offset:128
	global_load_dwordx4 v[168:171], v146, s[28:29] offset:160
	global_load_dwordx4 v[172:175], v146, s[28:29] offset:192
	global_load_dwordx4 v[176:179], v146, s[28:29] offset:224
	global_load_dwordx4 v[180:183], v146, s[28:29] offset:256
	global_load_dwordx4 v[188:191], v146, s[28:29] offset:288
	global_load_dwordx4 v[192:195], v146, s[28:29] offset:320
	global_load_dwordx4 v[206:209], v146, s[28:29] offset:352
	global_load_dwordx4 v[210:213], v146, s[28:29] offset:384
	global_load_dwordx4 v[236:239], v146, s[28:29] offset:416
	global_load_dwordx4 v[240:243], v146, s[28:29] offset:448
	global_load_dwordx4 v[244:247], v146, s[28:29] offset:480
	v_pk_fma_f32 v[56:57], v[56:57], v[0:1], v[134:135] op_sel_hi:[1,0,1] neg_lo:[0,0,1] neg_hi:[0,0,1]
	v_pk_fma_f32 v[2:3], v[12:13], v[0:1], v[2:3] op_sel_hi:[1,0,1] neg_lo:[0,0,1] neg_hi:[0,0,1]
	v_pk_fma_f32 v[6:7], v[10:11], v[0:1], v[6:7] op_sel_hi:[1,0,1] neg_lo:[0,0,1] neg_hi:[0,0,1]
	v_add_f32_e32 v0, v136, v137
	v_add_f32_e32 v0, v0, v118
	v_lshl_add_u64 v[50:51], v[138:139], 0, v[150:151]
	v_pk_mul_f32 v[138:139], v[130:131], v[130:131]
	v_add_f32_e32 v0, v0, v119
	v_add_f32_e32 v0, v0, v138
	v_pk_mul_f32 v[134:135], v[56:57], v[56:57]
	v_add_f32_e32 v0, v0, v139
	v_add_f32_e32 v0, v0, v134
	v_pk_mul_f32 v[126:127], v[60:61], v[60:61]
	v_add_f32_e32 v0, v0, v135
	v_add_f32_e32 v0, v0, v126
	v_pk_mul_f32 v[128:129], v[54:55], v[54:55]
	v_add_f32_e32 v0, v0, v127
	v_add_f32_e32 v0, v0, v128
	v_pk_mul_f32 v[122:123], v[62:63], v[62:63]
	v_add_f32_e32 v0, v0, v129
	v_add_f32_e32 v0, v0, v122
	v_pk_mul_f32 v[124:125], v[58:59], v[58:59]
	v_add_f32_e32 v0, v0, v123
	v_add_f32_e32 v0, v0, v124
	v_pk_mul_f32 v[116:117], v[64:65], v[64:65]
	v_add_f32_e32 v0, v0, v125
	v_add_f32_e32 v0, v0, v116
	v_pk_mul_f32 v[120:121], v[36:37], v[36:37]
	v_add_f32_e32 v0, v0, v117
	v_add_f32_e32 v0, v0, v120
	v_pk_mul_f32 v[112:113], v[38:39], v[38:39]
	v_add_f32_e32 v0, v0, v121
	v_add_f32_e32 v0, v0, v112
	v_pk_mul_f32 v[114:115], v[34:35], v[34:35]
	v_add_f32_e32 v0, v0, v113
	v_add_f32_e32 v0, v0, v114
	v_pk_mul_f32 v[142:143], v[108:109], v[108:109]
	v_add_f32_e32 v0, v0, v115
	v_add_f32_e32 v0, v0, v142
	v_pk_mul_f32 v[140:141], v[110:111], v[110:111]
	v_add_f32_e32 v0, v0, v143
	v_add_f32_e32 v0, v0, v140
	v_pk_mul_f32 v[144:145], v[104:105], v[104:105]
	v_add_f32_e32 v0, v0, v141
	v_add_f32_e32 v0, v0, v144
	v_pk_mul_f32 v[106:107], v[48:49], v[48:49]
	v_add_f32_e32 v0, v0, v145
	v_add_f32_e32 v0, v0, v106
	v_pk_mul_f32 v[100:101], v[46:47], v[46:47]
	v_add_f32_e32 v0, v0, v107
	v_add_f32_e32 v0, v0, v100
	v_pk_mul_f32 v[102:103], v[42:43], v[42:43]
	v_add_f32_e32 v0, v0, v101
	v_add_f32_e32 v0, v0, v102
	v_pk_mul_f32 v[96:97], v[44:45], v[44:45]
	v_add_f32_e32 v0, v0, v103
	v_add_f32_e32 v0, v0, v96
	v_pk_mul_f32 v[98:99], v[40:41], v[40:41]
	v_add_f32_e32 v0, v0, v97
	v_add_f32_e32 v0, v0, v98
	v_pk_mul_f32 v[92:93], v[28:29], v[28:29]
	v_add_f32_e32 v0, v0, v99
	v_add_f32_e32 v0, v0, v92
	v_pk_mul_f32 v[94:95], v[24:25], v[24:25]
	v_add_f32_e32 v0, v0, v93
	v_add_f32_e32 v0, v0, v94
	v_pk_mul_f32 v[30:31], v[26:27], v[26:27]
	v_add_f32_e32 v0, v0, v95
	v_add_f32_e32 v0, v0, v30
	v_pk_mul_f32 v[32:33], v[20:21], v[20:21]
	v_add_f32_e32 v0, v0, v31
	v_add_f32_e32 v0, v0, v32
	v_pk_mul_f32 v[84:85], v[22:23], v[22:23]
	v_add_f32_e32 v0, v0, v33
	v_add_f32_e32 v0, v0, v84
	v_pk_mul_f32 v[86:87], v[18:19], v[18:19]
	v_add_f32_e32 v0, v0, v85
	v_add_f32_e32 v0, v0, v86
	v_pk_mul_f32 v[80:81], v[8:9], v[8:9]
	v_add_f32_e32 v0, v0, v87
	v_add_f32_e32 v0, v0, v80
	v_pk_mul_f32 v[82:83], v[4:5], v[4:5]
	v_add_f32_e32 v0, v0, v81
	v_add_f32_e32 v0, v0, v82
	v_pk_mul_f32 v[10:11], v[6:7], v[6:7]
	v_add_f32_e32 v0, v0, v83
	v_add_f32_e32 v0, v0, v10
	v_pk_mul_f32 v[12:13], v[2:3], v[2:3]
	v_add_f32_e32 v0, v0, v11
	v_add_f32_e32 v0, v0, v12
	v_add_f32_e32 v0, v0, v13
	v_add_f32_e32 v0, v0, v70
	v_add_f32_e32 v0, v0, v71
	v_add_f32_e32 v0, v0, v74
	v_add_f32_e32 v0, v0, v75
	ds_bpermute_b32 v10, v147, v0
	s_waitcnt lgkmcnt(0)
	v_add_f32_e32 v0, v0, v10
	v_fmamk_f32 v0, v0, 0x3c000000, v187
	v_cmp_gt_f32_e32 vcc, s82, v0
	v_mul_f32_e32 v10, 0x4b800000, v0
	s_nop 0
	v_cndmask_b32_e32 v0, v0, v10, vcc
	v_rsq_f32_e32 v0, v0
	s_nop 0
	v_mul_f32_e32 v10, 0x45800000, v0
	v_cndmask_b32_e32 v0, v0, v10, vcc
	v_mul_f32_e32 v0, v73, v0
	v_pk_mul_f32 v[10:11], v[132:133], v[0:1] op_sel_hi:[1,0]
	v_pk_mul_f32 v[12:13], v[52:53], v[0:1] op_sel_hi:[1,0]
	s_waitcnt vmcnt(0)
	v_pk_mul_f32 v[10:11], v[14:15], v[10:11]
	v_pk_mul_f32 v[12:13], v[16:17], v[12:13]
	v_cvt_pk_bf16_f32 v10, v10, v11
	v_cvt_pk_bf16_f32 v11, v12, v13
	global_store_dwordx2 v[50:51], v[10:11], off
	s_nop 1
	v_mov_b32_e32 v10, v152
	v_mov_b32_e32 v11, v153
	v_mov_b32_e32 v12, v154
	v_mov_b32_e32 v13, v155
	v_pk_mul_f32 v[14:15], v[130:131], v[0:1] op_sel_hi:[1,0]
	v_pk_mul_f32 v[8:9], v[8:9], v[0:1] op_sel_hi:[1,0]
	v_pk_mul_f32 v[4:5], v[4:5], v[0:1] op_sel_hi:[1,0]
	v_pk_mul_f32 v[2:3], v[2:3], v[0:1] op_sel_hi:[1,0]
	s_nop 0
	v_pk_mul_f32 v[10:11], v[10:11], v[14:15]
	v_pk_mul_f32 v[14:15], v[56:57], v[0:1] op_sel_hi:[1,0]
	v_cvt_pk_bf16_f32 v10, v10, v11
	v_pk_mul_f32 v[12:13], v[12:13], v[14:15]
	v_pk_mul_f32 v[14:15], v[60:61], v[0:1] op_sel_hi:[1,0]
	v_cvt_pk_bf16_f32 v11, v12, v13
	global_store_dwordx2 v[50:51], v[10:11], off offset:16
	s_nop 1
	v_mov_b32_e32 v10, v156
	v_mov_b32_e32 v11, v157
	v_mov_b32_e32 v12, v158
	v_mov_b32_e32 v13, v159
	s_nop 0
	v_pk_mul_f32 v[10:11], v[14:15], v[10:11]
	v_pk_mul_f32 v[14:15], v[54:55], v[0:1] op_sel_hi:[1,0]
	v_cvt_pk_bf16_f32 v10, v10, v11
	v_pk_mul_f32 v[12:13], v[14:15], v[12:13]
	v_pk_mul_f32 v[14:15], v[62:63], v[0:1] op_sel_hi:[1,0]
	v_cvt_pk_bf16_f32 v11, v12, v13
	global_store_dwordx2 v[50:51], v[10:11], off offset:32
	s_nop 1
	v_mov_b32_e32 v10, v160
	v_mov_b32_e32 v11, v161
	v_mov_b32_e32 v12, v162
	v_mov_b32_e32 v13, v163
	s_nop 0
	v_pk_mul_f32 v[10:11], v[14:15], v[10:11]
	v_pk_mul_f32 v[14:15], v[58:59], v[0:1] op_sel_hi:[1,0]
	v_cvt_pk_bf16_f32 v10, v10, v11
	v_pk_mul_f32 v[12:13], v[14:15], v[12:13]
	v_pk_mul_f32 v[14:15], v[64:65], v[0:1] op_sel_hi:[1,0]
	v_cvt_pk_bf16_f32 v11, v12, v13
	global_store_dwordx2 v[50:51], v[10:11], off offset:48
	s_nop 1
	v_mov_b32_e32 v10, v164
	v_mov_b32_e32 v11, v165
	v_mov_b32_e32 v12, v166
	v_mov_b32_e32 v13, v167
	s_nop 0
	v_pk_mul_f32 v[10:11], v[14:15], v[10:11]
	v_pk_mul_f32 v[14:15], v[36:37], v[0:1] op_sel_hi:[1,0]
	v_cvt_pk_bf16_f32 v10, v10, v11
	v_pk_mul_f32 v[12:13], v[14:15], v[12:13]
	v_pk_mul_f32 v[14:15], v[38:39], v[0:1] op_sel_hi:[1,0]
	v_cvt_pk_bf16_f32 v11, v12, v13
	global_store_dwordx2 v[50:51], v[10:11], off offset:64
	s_nop 1
	v_mov_b32_e32 v10, v168
	v_mov_b32_e32 v11, v169
	v_mov_b32_e32 v12, v170
	v_mov_b32_e32 v13, v171
	s_nop 0
	v_pk_mul_f32 v[10:11], v[14:15], v[10:11]
	v_pk_mul_f32 v[14:15], v[34:35], v[0:1] op_sel_hi:[1,0]
	v_cvt_pk_bf16_f32 v10, v10, v11
	v_pk_mul_f32 v[12:13], v[14:15], v[12:13]
	v_pk_mul_f32 v[14:15], v[108:109], v[0:1] op_sel_hi:[1,0]
	v_cvt_pk_bf16_f32 v11, v12, v13
	global_store_dwordx2 v[50:51], v[10:11], off offset:80
	s_nop 1
	v_mov_b32_e32 v10, v172
	v_mov_b32_e32 v11, v173
	v_mov_b32_e32 v12, v174
	v_mov_b32_e32 v13, v175
	s_nop 0
	v_pk_mul_f32 v[10:11], v[14:15], v[10:11]
	v_pk_mul_f32 v[14:15], v[110:111], v[0:1] op_sel_hi:[1,0]
	v_cvt_pk_bf16_f32 v10, v10, v11
	v_pk_mul_f32 v[12:13], v[14:15], v[12:13]
	v_pk_mul_f32 v[14:15], v[104:105], v[0:1] op_sel_hi:[1,0]
	v_cvt_pk_bf16_f32 v11, v12, v13
	global_store_dwordx2 v[50:51], v[10:11], off offset:96
	s_nop 1
	v_mov_b32_e32 v10, v176
	v_mov_b32_e32 v11, v177
	v_mov_b32_e32 v12, v178
	v_mov_b32_e32 v13, v179
	s_nop 0
	v_pk_mul_f32 v[10:11], v[14:15], v[10:11]
	v_pk_mul_f32 v[14:15], v[48:49], v[0:1] op_sel_hi:[1,0]
	v_cvt_pk_bf16_f32 v10, v10, v11
	v_pk_mul_f32 v[12:13], v[14:15], v[12:13]
	v_pk_mul_f32 v[14:15], v[46:47], v[0:1] op_sel_hi:[1,0]
	v_cvt_pk_bf16_f32 v11, v12, v13
	global_store_dwordx2 v[50:51], v[10:11], off offset:112
	s_nop 1
	v_mov_b32_e32 v10, v180
	v_mov_b32_e32 v11, v181
	v_mov_b32_e32 v12, v182
	v_mov_b32_e32 v13, v183
	s_nop 0
	v_pk_mul_f32 v[10:11], v[14:15], v[10:11]
	v_pk_mul_f32 v[14:15], v[42:43], v[0:1] op_sel_hi:[1,0]
	v_cvt_pk_bf16_f32 v10, v10, v11
	v_pk_mul_f32 v[12:13], v[14:15], v[12:13]
	v_pk_mul_f32 v[14:15], v[44:45], v[0:1] op_sel_hi:[1,0]
	v_cvt_pk_bf16_f32 v11, v12, v13
	global_store_dwordx2 v[50:51], v[10:11], off offset:128
	s_nop 1
	v_mov_b32_e32 v10, v188
	v_mov_b32_e32 v11, v189
	v_mov_b32_e32 v12, v190
	v_mov_b32_e32 v13, v191
	s_nop 0
	v_pk_mul_f32 v[10:11], v[14:15], v[10:11]
	v_pk_mul_f32 v[14:15], v[40:41], v[0:1] op_sel_hi:[1,0]
	v_cvt_pk_bf16_f32 v10, v10, v11
	v_pk_mul_f32 v[12:13], v[14:15], v[12:13]
	v_pk_mul_f32 v[14:15], v[28:29], v[0:1] op_sel_hi:[1,0]
	v_cvt_pk_bf16_f32 v11, v12, v13
	global_store_dwordx2 v[50:51], v[10:11], off offset:144
	s_nop 1
	v_mov_b32_e32 v10, v192
	v_mov_b32_e32 v11, v193
	v_mov_b32_e32 v12, v194
	v_mov_b32_e32 v13, v195
	s_nop 0
	v_pk_mul_f32 v[10:11], v[14:15], v[10:11]
	v_pk_mul_f32 v[14:15], v[24:25], v[0:1] op_sel_hi:[1,0]
	v_cvt_pk_bf16_f32 v10, v10, v11
	v_pk_mul_f32 v[12:13], v[14:15], v[12:13]
	v_pk_mul_f32 v[14:15], v[26:27], v[0:1] op_sel_hi:[1,0]
	v_cvt_pk_bf16_f32 v11, v12, v13
	global_store_dwordx2 v[50:51], v[10:11], off offset:160
	s_nop 1
	v_mov_b32_e32 v10, v206
	v_mov_b32_e32 v11, v207
	v_mov_b32_e32 v12, v208
	v_mov_b32_e32 v13, v209
	s_nop 0
	v_pk_mul_f32 v[10:11], v[14:15], v[10:11]
	v_pk_mul_f32 v[14:15], v[20:21], v[0:1] op_sel_hi:[1,0]
	v_cvt_pk_bf16_f32 v10, v10, v11
	v_pk_mul_f32 v[12:13], v[14:15], v[12:13]
	v_pk_mul_f32 v[14:15], v[22:23], v[0:1] op_sel_hi:[1,0]
	v_cvt_pk_bf16_f32 v11, v12, v13
	global_store_dwordx2 v[50:51], v[10:11], off offset:176
	s_nop 1
	v_mov_b32_e32 v10, v210
	v_mov_b32_e32 v11, v211
	v_mov_b32_e32 v12, v212
	v_mov_b32_e32 v13, v213
	s_nop 0
	v_pk_mul_f32 v[10:11], v[14:15], v[10:11]
	v_pk_mul_f32 v[14:15], v[18:19], v[0:1] op_sel_hi:[1,0]
	v_cvt_pk_bf16_f32 v10, v10, v11
	v_pk_mul_f32 v[12:13], v[14:15], v[12:13]
	s_nop 0
	v_cvt_pk_bf16_f32 v11, v12, v13
	global_store_dwordx2 v[50:51], v[10:11], off offset:192
	s_nop 1
	v_mov_b32_e32 v10, v236
	v_mov_b32_e32 v11, v237
	v_mov_b32_e32 v12, v238
	v_mov_b32_e32 v13, v239
	s_nop 0
	v_pk_mul_f32 v[8:9], v[8:9], v[10:11]
	v_pk_mul_f32 v[4:5], v[4:5], v[12:13]
	v_cvt_pk_bf16_f32 v8, v8, v9
	v_cvt_pk_bf16_f32 v9, v4, v5
	global_store_dwordx2 v[50:51], v[8:9], off offset:208
	s_nop 1
	v_mov_b32_e32 v8, v240
	v_mov_b32_e32 v9, v241
	v_mov_b32_e32 v10, v242
	v_mov_b32_e32 v11, v243
	v_pk_mul_f32 v[4:5], v[6:7], v[0:1] op_sel_hi:[1,0]
	v_pk_mul_f32 v[6:7], v[66:67], v[0:1] op_sel_hi:[1,0]
	s_nop 0
	v_pk_mul_f32 v[4:5], v[4:5], v[8:9]
	v_pk_mul_f32 v[2:3], v[2:3], v[10:11]
	v_cvt_pk_bf16_f32 v4, v4, v5
	v_cvt_pk_bf16_f32 v5, v2, v3
	global_store_dwordx2 v[50:51], v[4:5], off offset:224
	s_nop 1
	v_mov_b32_e32 v2, v244
	v_mov_b32_e32 v3, v245
	v_mov_b32_e32 v4, v246
	v_mov_b32_e32 v5, v247
	s_nop 0
	v_pk_mul_f32 v[2:3], v[6:7], v[2:3]
	v_pk_mul_f32 v[6:7], v[68:69], v[0:1] op_sel_hi:[1,0]
	v_cvt_pk_bf16_f32 v2, v2, v3
	v_pk_mul_f32 v[4:5], v[6:7], v[4:5]
	s_nop 0
	v_cvt_pk_bf16_f32 v3, v4, v5
	global_store_dwordx2 v[50:51], v[2:3], off offset:240
